# grid barrier: acquire-side L1 invalidate issued with the arrival atomic (overlaps its round trip) instead of after the release is observed
# speedup vs baseline: 1.0107x; 1.0030x over previous
; __device__ __forceinline__ unsigned xb_add(unsigned* p, unsigned v) { return __hip_atomic_fetch_add(p, v, __ATOMIC_RELAXED, __HIP_MEMORY_SCOPE_AGENT); }
; __device__ __forceinline__ void xcd_barrier(const XcdBarrier& b) {
;     ...
;         const unsigned old = xb_add(&bar[XB_XSUB(b.x)], 1u);
;         const unsigned gen = old / nloc;
;         if (old + 1u == (gen + 1u) * nloc) {
.LBB0_118:
	s_lshl_b32 s3, s3, 8
	s_mov_b64 s[10:11], exec
	s_add_u32 s3, s6, s3
	s_addc_u32 s9, s7, 0
	v_mbcnt_lo_u32_b32 v1, s10, 0
	s_add_u32 s8, s3, 0x2e800000
	v_mbcnt_hi_u32_b32 v1, s11, v1
	s_addc_u32 s9, s9, 0
	v_cmp_eq_u32_e32 vcc, 0, v1
	s_and_saveexec_b64 s[12:13], vcc
	s_cbranch_execz .LBB0_120
	s_bcnt1_i32_b64 s3, s[10:11]
	v_mov_b32_e32 v3, 0x1000
	v_mov_b32_e32 v4, s3
	global_atomic_add v3, v3, v4, s[8:9] offset:1024 sc0
	buffer_inv sc1

; __device__ __forceinline__ unsigned xb_ld(unsigned* p)              { return __hip_atomic_load(p, __ATOMIC_RELAXED, __HIP_MEMORY_SCOPE_AGENT); }
; #define XB_SPIN(cond, bar) do { unsigned _sp = 0; while (cond) { __builtin_amdgcn_s_sleep(1); \
;     if ((++_sp & 255u) == 0u) { if (xb_ld(&(bar)[XB_TMO])) break; if (_sp > XB_SPIN_CAP) { atomicAdd(&(bar)[XB_TMO], 1u); break; } } } } while (0)
; __device__ __forceinline__ void xcd_barrier(const XcdBarrier& b) {
;     ...
;             XB_SPIN(xb_ld(&bar[XB_XGEN(b.x)]) == gen, bar);
;             __builtin_amdgcn_fence(__ATOMIC_ACQUIRE, "agent");
;             asm volatile("s_waitcnt vmcnt(0)" ::: "memory");
.LBB0_133:
	s_or_b64 exec, exec, s[12:13]
	s_waitcnt vmcnt(0)
	s_waitcnt vmcnt(0)

; __device__ __forceinline__ unsigned xb_add(unsigned* p, unsigned v) { return __hip_atomic_fetch_add(p, v, __ATOMIC_RELAXED, __HIP_MEMORY_SCOPE_AGENT); }
; __device__ __forceinline__ void xcd_barrier(const XcdBarrier& b) {
;     ...
;             __builtin_amdgcn_fence(__ATOMIC_ACQUIRE, "agent");
;             xb_add(&bar[XB_XGEN(b.x)], 1u);
;             asm volatile("s_waitcnt vmcnt(0)" ::: "memory");
.LBB0_151:
	s_or_b64 exec, exec, s[6:7]
	s_mov_b64 s[6:7], exec
	v_mbcnt_lo_u32_b32 v0, s6, 0
	v_mbcnt_hi_u32_b32 v0, s7, v0
	v_cmp_eq_u32_e32 vcc, 0, v0
	s_waitcnt vmcnt(0)
	s_and_saveexec_b64 s[10:11], vcc
	s_cbranch_execz .LBB0_153
	s_bcnt1_i32_b64 s3, s[6:7]
	v_mov_b32_e32 v0, 0x2000
	v_mov_b32_e32 v1, s3

; __device__ __forceinline__ unsigned xb_add(unsigned* p, unsigned v) { return __hip_atomic_fetch_add(p, v, __ATOMIC_RELAXED, __HIP_MEMORY_SCOPE_AGENT); }
; __device__ __forceinline__ void xcd_barrier(const XcdBarrier& b) {
;     ...
;         const unsigned old = xb_add(&bar[XB_XSUB(b.x)], 1u);
;         const unsigned gen = old / nloc;
;         if (old + 1u == (gen + 1u) * nloc) {
.LBB0_204:
	s_lshl_b32 s3, s3, 8
	s_mov_b64 s[10:11], exec
	s_add_u32 s3, s6, s3
	s_addc_u32 s9, s7, 0
	v_mbcnt_lo_u32_b32 v1, s10, 0
	s_add_u32 s8, s3, 0x2e800000
	v_mbcnt_hi_u32_b32 v1, s11, v1
	s_addc_u32 s9, s9, 0
	v_cmp_eq_u32_e32 vcc, 0, v1
	s_and_saveexec_b64 s[12:13], vcc
	s_cbranch_execz .LBB0_206
	s_bcnt1_i32_b64 s3, s[10:11]
	v_mov_b32_e32 v3, s3
	v_mov_b32_e32 v4, 0x1000
	global_atomic_add v3, v4, v3, s[8:9] offset:1024 sc0
	buffer_inv sc1

; __device__ __forceinline__ unsigned xb_add(unsigned* p, unsigned v) { return __hip_atomic_fetch_add(p, v, __ATOMIC_RELAXED, __HIP_MEMORY_SCOPE_AGENT); }
; __device__ __forceinline__ void xcd_barrier(const XcdBarrier& b) {
;     ...
;             __builtin_amdgcn_fence(__ATOMIC_ACQUIRE, "agent");
;             xb_add(&bar[XB_XGEN(b.x)], 1u);
;             asm volatile("s_waitcnt vmcnt(0)" ::: "memory");
.LBB0_237:
	s_or_b64 exec, exec, s[6:7]
	s_mov_b64 s[6:7], exec
	v_mbcnt_lo_u32_b32 v0, s6, 0
	v_mbcnt_hi_u32_b32 v0, s7, v0
	v_cmp_eq_u32_e32 vcc, 0, v0
	s_waitcnt vmcnt(0)
	s_and_saveexec_b64 s[10:11], vcc
	s_cbranch_execz .LBB0_239
	s_bcnt1_i32_b64 s3, s[6:7]
	v_mov_b32_e32 v0, s3

; __device__ __forceinline__ unsigned xb_add(unsigned* p, unsigned v) { return __hip_atomic_fetch_add(p, v, __ATOMIC_RELAXED, __HIP_MEMORY_SCOPE_AGENT); }
; __device__ __forceinline__ void xcd_barrier(const XcdBarrier& b) {
;     ...
;         const unsigned old = xb_add(&bar[XB_XSUB(b.x)], 1u);
;         const unsigned gen = old / nloc;
;         if (old + 1u == (gen + 1u) * nloc) {
.LBB0_304:
	s_lshl_b32 s2, s2, 8
	s_mov_b64 s[10:11], exec
	s_add_u32 s2, s6, s2
	s_addc_u32 s3, s7, 0
	v_mbcnt_lo_u32_b32 v1, s10, 0
	s_add_u32 s8, s2, 0x2e800000
	v_mbcnt_hi_u32_b32 v1, s11, v1
	s_addc_u32 s9, s3, 0
	v_cmp_eq_u32_e32 vcc, 0, v1
	s_and_saveexec_b64 s[12:13], vcc
	s_cbranch_execz .LBB0_306
	s_bcnt1_i32_b64 s2, s[10:11]
	v_mov_b32_e32 v3, s2
	v_mov_b32_e32 v4, 0x1000
	global_atomic_add v3, v4, v3, s[8:9] offset:1024 sc0
	buffer_inv sc1

; __device__ __forceinline__ unsigned xb_add(unsigned* p, unsigned v) { return __hip_atomic_fetch_add(p, v, __ATOMIC_RELAXED, __HIP_MEMORY_SCOPE_AGENT); }
; __device__ __forceinline__ void xcd_barrier(const XcdBarrier& b) {
;     ...
;             __builtin_amdgcn_fence(__ATOMIC_ACQUIRE, "agent");
;             xb_add(&bar[XB_XGEN(b.x)], 1u);
;             asm volatile("s_waitcnt vmcnt(0)" ::: "memory");
.LBB0_337:
	s_or_b64 exec, exec, s[6:7]
	s_mov_b64 s[6:7], exec
	v_mbcnt_lo_u32_b32 v0, s6, 0
	v_mbcnt_hi_u32_b32 v0, s7, v0
	v_cmp_eq_u32_e32 vcc, 0, v0
	s_waitcnt vmcnt(0)
	s_and_saveexec_b64 s[10:11], vcc
	s_cbranch_execz .LBB0_339
	s_bcnt1_i32_b64 s2, s[6:7]
	v_mov_b32_e32 v0, s2

; __device__ __forceinline__ unsigned xb_add(unsigned* p, unsigned v) { return __hip_atomic_fetch_add(p, v, __ATOMIC_RELAXED, __HIP_MEMORY_SCOPE_AGENT); }
; __device__ __forceinline__ void xcd_barrier(const XcdBarrier& b) {
;     ...
;         const unsigned old = xb_add(&bar[XB_XSUB(b.x)], 1u);
;         const unsigned gen = old / nloc;
;         if (old + 1u == (gen + 1u) * nloc) {
.LBB0_670:
	s_lshl_b32 s3, s3, 8
	s_mov_b64 s[10:11], exec
	s_add_u32 s3, s6, s3
	s_addc_u32 s9, s7, 0
	v_mbcnt_lo_u32_b32 v1, s10, 0
	s_add_u32 s8, s3, 0x2e800000
	v_mbcnt_hi_u32_b32 v1, s11, v1
	s_addc_u32 s9, s9, 0
	v_cmp_eq_u32_e32 vcc, 0, v1
	s_and_saveexec_b64 s[14:15], vcc
	s_cbranch_execz .LBB0_672
	s_bcnt1_i32_b64 s3, s[10:11]
	v_mov_b32_e32 v3, s3
	v_mov_b32_e32 v4, 0x1000
	global_atomic_add v3, v4, v3, s[8:9] offset:1024 sc0
	buffer_inv sc1

; __device__ __forceinline__ unsigned xb_ld(unsigned* p)              { return __hip_atomic_load(p, __ATOMIC_RELAXED, __HIP_MEMORY_SCOPE_AGENT); }
; #define XB_SPIN(cond, bar) do { unsigned _sp = 0; while (cond) { __builtin_amdgcn_s_sleep(1); \
;     if ((++_sp & 255u) == 0u) { if (xb_ld(&(bar)[XB_TMO])) break; if (_sp > XB_SPIN_CAP) { atomicAdd(&(bar)[XB_TMO], 1u); break; } } } } while (0)
; __device__ __forceinline__ void xcd_barrier(const XcdBarrier& b) {
;     ...
;             XB_SPIN(xb_ld(&bar[XB_XGEN(b.x)]) == gen, bar);
;             __builtin_amdgcn_fence(__ATOMIC_ACQUIRE, "agent");
;             asm volatile("s_waitcnt vmcnt(0)" ::: "memory");
.LBB0_702:
	s_or_b64 exec, exec, s[14:15]
	s_waitcnt vmcnt(0)
	s_waitcnt vmcnt(0)

; __device__ __forceinline__ unsigned xb_add(unsigned* p, unsigned v) { return __hip_atomic_fetch_add(p, v, __ATOMIC_RELAXED, __HIP_MEMORY_SCOPE_AGENT); }
; __device__ __forceinline__ void xcd_barrier(const XcdBarrier& b) {
;     ...
;             __builtin_amdgcn_fence(__ATOMIC_ACQUIRE, "agent");
;             xb_add(&bar[XB_XGEN(b.x)], 1u);
;             asm volatile("s_waitcnt vmcnt(0)" ::: "memory");
.LBB0_1489:
	s_or_b64 exec, exec, s[6:7]
	s_mov_b64 s[6:7], exec
	v_mbcnt_lo_u32_b32 v0, s6, 0
	v_mbcnt_hi_u32_b32 v0, s7, v0
	v_cmp_eq_u32_e32 vcc, 0, v0
	s_waitcnt vmcnt(0)
	s_and_saveexec_b64 s[10:11], vcc
	s_cbranch_execnz .LBB0_1490
	s_getpc_b64 s[98:99]
